# gate/up H stores marked non-temporal (nt)
# speedup vs baseline: 1.0165x; 1.0165x over previous
.LBB0_1100:
	v_lshl_add_u32 v150, s3, 10, v148
	ds_read2_b32 v[152:153], v150 offset1:16
	v_lshl_or_b32 v140, s2, 7, v147
	s_lshl_b32 s2, s24, 8
	v_ashrrev_i32_e32 v141, 31, v140
	s_andn2_b64 vcc, exec, s[4:5]
	s_waitcnt lgkmcnt(0)
	v_pk_mul_f32 v[126:127], v[126:127], v[152:153] op_sel_hi:[1,0]
	v_pk_mul_f32 v[122:123], v[122:123], v[152:153] op_sel_hi:[1,0]
	v_mul_f32_e32 v151, 0xbfb8aa3b, v126
	v_exp_f32_e32 v151, v151
	v_pk_mul_f32 v[124:125], v[124:125], v[152:153] op_sel_hi:[1,0]
	v_pk_mul_f32 v[118:119], v[118:119], v[152:153] op_sel_hi:[1,0]
	v_pk_mul_f32 v[114:115], v[114:115], v[152:153] op_sel_hi:[1,0]
	v_add_f32_e32 v151, 1.0, v151
	v_rcp_f32_e32 v154, v151
	v_mul_f32_e32 v151, 0xbfb8aa3b, v127
	v_exp_f32_e32 v151, v151
	v_pk_mul_f32 v[116:117], v[116:117], v[152:153] op_sel_hi:[1,0]
	v_add_f32_e32 v151, 1.0, v151
	v_rcp_f32_e32 v155, v151
	s_nop 0
	v_pk_mul_f32 v[126:127], v[126:127], v[154:155]
	s_nop 0
	v_pk_mul_f32 v[122:123], v[122:123], v[126:127]
	v_pk_mul_f32 v[126:127], v[128:129], v[152:153] op_sel_hi:[1,0]
	s_nop 0
	v_mul_f32_e32 v128, 0xbfb8aa3b, v126
	v_mul_f32_e32 v129, 0xbfb8aa3b, v127
	v_exp_f32_e32 v128, v128
	v_exp_f32_e32 v129, v129
	v_add_f32_e32 v128, 1.0, v128
	v_add_f32_e32 v129, 1.0, v129
	v_rcp_f32_e32 v128, v128
	v_rcp_f32_e32 v129, v129
	s_nop 0
	v_pk_mul_f32 v[126:127], v[126:127], v[128:129]
	s_nop 0
	v_pk_mul_f32 v[124:125], v[124:125], v[126:127]
	v_mul_f32_e32 v126, 0xbfb8aa3b, v118
	v_mul_f32_e32 v127, 0xbfb8aa3b, v119
	v_exp_f32_e32 v126, v126
	v_exp_f32_e32 v127, v127
	v_add_f32_e32 v126, 1.0, v126
	v_add_f32_e32 v127, 1.0, v127
	v_rcp_f32_e32 v126, v126
	v_rcp_f32_e32 v127, v127
	s_nop 0
	v_pk_mul_f32 v[118:119], v[118:119], v[126:127]
	s_nop 0
	v_pk_mul_f32 v[114:115], v[114:115], v[118:119]
	v_pk_mul_f32 v[118:119], v[120:121], v[152:153] op_sel_hi:[1,0]
	s_nop 0
	v_mul_f32_e32 v120, 0xbfb8aa3b, v118
	v_mul_f32_e32 v121, 0xbfb8aa3b, v119
	v_exp_f32_e32 v120, v120
	v_exp_f32_e32 v121, v121
	v_add_f32_e32 v120, 1.0, v120
	v_add_f32_e32 v121, 1.0, v121
	v_rcp_f32_e32 v120, v120
	v_rcp_f32_e32 v121, v121
	s_nop 0
	v_pk_mul_f32 v[118:119], v[118:119], v[120:121]
	s_nop 0
	v_pk_mul_f32 v[116:117], v[116:117], v[118:119]
	v_cvt_pk_bf16_f32 v120, v122, v123
	v_cvt_pk_bf16_f32 v122, v114, v115
	v_add_u32_e32 v118, s2, v142
	v_mov_b64_e32 v[114:115], s[12:13]
	v_cvt_pk_bf16_f32 v121, v124, v125
	v_cvt_pk_bf16_f32 v123, v116, v117
	v_mad_i64_i32 v[124:125], s[24:25], v118, s63, v[114:115]
	v_lshlrev_b64 v[116:117], 1, v[140:141]
	v_lshl_add_u64 v[124:125], v[124:125], 0, v[116:117]
	global_store_dwordx4 v[124:125], v[120:123], off nt
	s_nop 1
	v_mov_b32_e32 v120, v153
	v_pk_mul_f32 v[110:111], v[110:111], v[120:121] op_sel_hi:[1,0]
	v_pk_mul_f32 v[106:107], v[106:107], v[120:121] op_sel_hi:[1,0]
	v_mul_f32_e32 v119, 0xbfb8aa3b, v110
	v_exp_f32_e32 v119, v119
	v_pk_mul_f32 v[108:109], v[108:109], v[120:121] op_sel_hi:[1,0]
	v_pk_mul_f32 v[102:103], v[102:103], v[120:121] op_sel_hi:[1,0]
	v_pk_mul_f32 v[98:99], v[98:99], v[120:121] op_sel_hi:[1,0]
	v_add_f32_e32 v119, 1.0, v119
	v_rcp_f32_e32 v122, v119
	v_mul_f32_e32 v119, 0xbfb8aa3b, v111
	v_exp_f32_e32 v119, v119
	v_pk_mul_f32 v[100:101], v[100:101], v[120:121] op_sel_hi:[1,0]
	v_add_f32_e32 v119, 1.0, v119
	v_rcp_f32_e32 v123, v119
	s_nop 0
	v_pk_mul_f32 v[110:111], v[110:111], v[122:123]
	s_nop 0
	v_pk_mul_f32 v[106:107], v[106:107], v[110:111]
	v_pk_mul_f32 v[110:111], v[112:113], v[120:121] op_sel_hi:[1,0]
	s_nop 0
	v_mul_f32_e32 v112, 0xbfb8aa3b, v110
	v_mul_f32_e32 v113, 0xbfb8aa3b, v111
	v_exp_f32_e32 v112, v112
	v_exp_f32_e32 v113, v113
	v_add_f32_e32 v112, 1.0, v112
	v_add_f32_e32 v113, 1.0, v113
	v_rcp_f32_e32 v112, v112
	v_rcp_f32_e32 v113, v113
	s_nop 0
	v_pk_mul_f32 v[110:111], v[110:111], v[112:113]
	s_nop 0
	v_pk_mul_f32 v[108:109], v[108:109], v[110:111]
	v_mul_f32_e32 v110, 0xbfb8aa3b, v102
	v_mul_f32_e32 v111, 0xbfb8aa3b, v103
	v_exp_f32_e32 v110, v110
	v_exp_f32_e32 v111, v111
	v_add_f32_e32 v110, 1.0, v110
	v_add_f32_e32 v111, 1.0, v111
	v_rcp_f32_e32 v110, v110
	v_rcp_f32_e32 v111, v111
	s_nop 0
	v_pk_mul_f32 v[102:103], v[102:103], v[110:111]
	s_nop 0
	v_pk_mul_f32 v[102:103], v[98:99], v[102:103]
	v_pk_mul_f32 v[98:99], v[104:105], v[120:121] op_sel_hi:[1,0]
	s_nop 0
	v_mul_f32_e32 v104, 0xbfb8aa3b, v98
	v_mul_f32_e32 v105, 0xbfb8aa3b, v99
	v_exp_f32_e32 v104, v104
	v_exp_f32_e32 v105, v105
	v_add_f32_e32 v104, 1.0, v104
	v_add_f32_e32 v105, 1.0, v105
	v_rcp_f32_e32 v104, v104
	v_rcp_f32_e32 v105, v105
	s_nop 0
	v_pk_mul_f32 v[98:99], v[98:99], v[104:105]
	s_nop 0
	v_pk_mul_f32 v[104:105], v[100:101], v[98:99]
	v_cvt_pk_bf16_f32 v100, v102, v103
	v_add_u32_e32 v102, s2, v144
	v_mad_i64_i32 v[102:103], s[24:25], v102, s63, v[114:115]
	v_cvt_pk_bf16_f32 v98, v106, v107
	v_cvt_pk_bf16_f32 v99, v108, v109
	v_cvt_pk_bf16_f32 v101, v104, v105
	v_lshl_add_u64 v[102:103], v[102:103], 0, v[116:117]
	global_store_dwordx4 v[102:103], v[98:101], off nt
	ds_read2_b32 v[98:99], v150 offset0:32 offset1:48
	s_waitcnt lgkmcnt(0)
	v_pk_mul_f32 v[94:95], v[94:95], v[98:99] op_sel_hi:[1,0]
	s_nop 0
	v_mul_f32_e32 v100, 0xbfb8aa3b, v94
	v_mul_f32_e32 v101, 0xbfb8aa3b, v95
	v_exp_f32_e32 v100, v100
	v_exp_f32_e32 v101, v101
	v_pk_mul_f32 v[90:91], v[90:91], v[98:99] op_sel_hi:[1,0]
	v_pk_mul_f32 v[92:93], v[92:93], v[98:99] op_sel_hi:[1,0]
	v_add_f32_e32 v100, 1.0, v100
	v_add_f32_e32 v101, 1.0, v101
	v_rcp_f32_e32 v100, v100
	v_rcp_f32_e32 v101, v101
	v_pk_mul_f32 v[86:87], v[86:87], v[98:99] op_sel_hi:[1,0]
	v_pk_mul_f32 v[82:83], v[82:83], v[98:99] op_sel_hi:[1,0]
	v_pk_mul_f32 v[84:85], v[84:85], v[98:99] op_sel_hi:[1,0]
	v_pk_mul_f32 v[94:95], v[94:95], v[100:101]
	s_nop 0
	v_pk_mul_f32 v[90:91], v[90:91], v[94:95]
	v_pk_mul_f32 v[94:95], v[96:97], v[98:99] op_sel_hi:[1,0]
	s_nop 0
	v_mul_f32_e32 v96, 0xbfb8aa3b, v94
	v_mul_f32_e32 v97, 0xbfb8aa3b, v95
	v_exp_f32_e32 v96, v96
	v_exp_f32_e32 v97, v97
	v_add_f32_e32 v96, 1.0, v96
	v_add_f32_e32 v97, 1.0, v97
	v_rcp_f32_e32 v96, v96
	v_rcp_f32_e32 v97, v97
	s_nop 0
	v_pk_mul_f32 v[94:95], v[94:95], v[96:97]
	s_nop 0
	v_pk_mul_f32 v[92:93], v[92:93], v[94:95]
	v_mul_f32_e32 v94, 0xbfb8aa3b, v86
	v_mul_f32_e32 v95, 0xbfb8aa3b, v87
	v_exp_f32_e32 v94, v94
	v_exp_f32_e32 v95, v95
	v_add_f32_e32 v94, 1.0, v94
	v_add_f32_e32 v95, 1.0, v95
	v_rcp_f32_e32 v94, v94
	v_rcp_f32_e32 v95, v95
	s_nop 0
	v_pk_mul_f32 v[86:87], v[86:87], v[94:95]
	s_nop 0
	v_pk_mul_f32 v[86:87], v[82:83], v[86:87]
	v_pk_mul_f32 v[82:83], v[88:89], v[98:99] op_sel_hi:[1,0]
	s_nop 0
	v_mul_f32_e32 v88, 0xbfb8aa3b, v82
	v_mul_f32_e32 v89, 0xbfb8aa3b, v83
	v_exp_f32_e32 v88, v88
	v_exp_f32_e32 v89, v89
	v_add_f32_e32 v88, 1.0, v88
	v_add_f32_e32 v89, 1.0, v89
	v_rcp_f32_e32 v88, v88
	v_rcp_f32_e32 v89, v89
	s_nop 0
	v_pk_mul_f32 v[82:83], v[82:83], v[88:89]
	s_nop 0
	v_pk_mul_f32 v[88:89], v[84:85], v[82:83]
	v_cvt_pk_bf16_f32 v84, v86, v87
	v_add_u32_e32 v86, s2, v145
	v_mad_i64_i32 v[86:87], s[24:25], v86, s63, v[114:115]
	v_cvt_pk_bf16_f32 v82, v90, v91
	v_cvt_pk_bf16_f32 v83, v92, v93
	v_cvt_pk_bf16_f32 v85, v88, v89
	v_lshl_add_u64 v[86:87], v[86:87], 0, v[116:117]
	global_store_dwordx4 v[86:87], v[82:85], off nt
	s_mov_b64 s[24:25], -1
	s_nop 0
	v_mov_b32_e32 v82, v99
	v_pk_mul_f32 v[78:79], v[78:79], v[82:83] op_sel_hi:[1,0]
	s_nop 0
	v_mul_f32_e32 v83, 0xbfb8aa3b, v78
	v_exp_f32_e32 v83, v83
	s_nop 0
	v_add_f32_e32 v83, 1.0, v83
	v_rcp_f32_e32 v84, v83
	v_mul_f32_e32 v83, 0xbfb8aa3b, v79
	v_exp_f32_e32 v83, v83
	s_nop 0
	v_add_f32_e32 v83, 1.0, v83
	v_rcp_f32_e32 v85, v83
	v_pk_mul_f32 v[74:75], v[74:75], v[82:83] op_sel_hi:[1,0]
	v_pk_mul_f32 v[76:77], v[76:77], v[82:83] op_sel_hi:[1,0]
	v_pk_mul_f32 v[70:71], v[70:71], v[82:83] op_sel_hi:[1,0]
	v_pk_mul_f32 v[78:79], v[78:79], v[84:85]
	v_pk_mul_f32 v[66:67], v[66:67], v[82:83] op_sel_hi:[1,0]
	v_pk_mul_f32 v[74:75], v[74:75], v[78:79]
	v_pk_mul_f32 v[78:79], v[80:81], v[82:83] op_sel_hi:[1,0]
	v_pk_mul_f32 v[68:69], v[68:69], v[82:83] op_sel_hi:[1,0]
	v_mul_f32_e32 v80, 0xbfb8aa3b, v78
	v_mul_f32_e32 v81, 0xbfb8aa3b, v79
	v_exp_f32_e32 v80, v80
	v_exp_f32_e32 v81, v81
	v_add_f32_e32 v80, 1.0, v80
	v_add_f32_e32 v81, 1.0, v81
	v_rcp_f32_e32 v80, v80
	v_rcp_f32_e32 v81, v81
	s_nop 0
	v_pk_mul_f32 v[78:79], v[78:79], v[80:81]
	s_nop 0
	v_pk_mul_f32 v[76:77], v[76:77], v[78:79]
	v_mul_f32_e32 v78, 0xbfb8aa3b, v70
	v_mul_f32_e32 v79, 0xbfb8aa3b, v71
	v_exp_f32_e32 v78, v78
	v_exp_f32_e32 v79, v79
	v_add_f32_e32 v78, 1.0, v78
	v_add_f32_e32 v79, 1.0, v79
	v_rcp_f32_e32 v78, v78
	v_rcp_f32_e32 v79, v79
	s_nop 0
	v_pk_mul_f32 v[70:71], v[70:71], v[78:79]
	s_nop 0
	v_pk_mul_f32 v[70:71], v[66:67], v[70:71]
	v_pk_mul_f32 v[66:67], v[72:73], v[82:83] op_sel_hi:[1,0]
	s_nop 0
	v_mul_f32_e32 v72, 0xbfb8aa3b, v66
	v_mul_f32_e32 v73, 0xbfb8aa3b, v67
	v_exp_f32_e32 v72, v72
	v_exp_f32_e32 v73, v73
	v_add_f32_e32 v72, 1.0, v72
	v_add_f32_e32 v73, 1.0, v73
	v_rcp_f32_e32 v72, v72
	v_rcp_f32_e32 v73, v73
	s_nop 0
	v_pk_mul_f32 v[66:67], v[66:67], v[72:73]
	s_nop 0
	v_pk_mul_f32 v[72:73], v[68:69], v[66:67]
	v_cvt_pk_bf16_f32 v68, v70, v71
	v_add_u32_e32 v70, s2, v146
	v_mad_i64_i32 v[70:71], s[2:3], v70, s63, v[114:115]
	v_cvt_pk_bf16_f32 v66, v74, v75
	v_cvt_pk_bf16_f32 v67, v76, v77
	v_cvt_pk_bf16_f32 v69, v72, v73
	v_lshl_add_u64 v[70:71], v[70:71], 0, v[116:117]
	global_store_dwordx4 v[70:71], v[66:69], off nt
	ds_read2_b32 v[66:67], v150 offset0:128 offset1:144
	s_waitcnt lgkmcnt(0)
	v_pk_mul_f32 v[62:63], v[62:63], v[66:67] op_sel_hi:[1,0]
	s_nop 0
	v_mul_f32_e32 v68, 0xbfb8aa3b, v62
	v_mul_f32_e32 v69, 0xbfb8aa3b, v63
	v_exp_f32_e32 v68, v68
	v_exp_f32_e32 v69, v69
	v_pk_mul_f32 v[58:59], v[58:59], v[66:67] op_sel_hi:[1,0]
	v_pk_mul_f32 v[60:61], v[60:61], v[66:67] op_sel_hi:[1,0]
	v_add_f32_e32 v68, 1.0, v68
	v_add_f32_e32 v69, 1.0, v69
	v_rcp_f32_e32 v68, v68
	v_rcp_f32_e32 v69, v69
	v_pk_mul_f32 v[54:55], v[54:55], v[66:67] op_sel_hi:[1,0]
	v_pk_mul_f32 v[50:51], v[50:51], v[66:67] op_sel_hi:[1,0]
	v_pk_mul_f32 v[52:53], v[52:53], v[66:67] op_sel_hi:[1,0]
	v_pk_mul_f32 v[62:63], v[62:63], v[68:69]
	s_nop 0
	v_pk_mul_f32 v[58:59], v[58:59], v[62:63]
	v_pk_mul_f32 v[62:63], v[64:65], v[66:67] op_sel_hi:[1,0]
	s_nop 0
	v_mul_f32_e32 v64, 0xbfb8aa3b, v62
	v_mul_f32_e32 v65, 0xbfb8aa3b, v63
	v_exp_f32_e32 v64, v64
	v_exp_f32_e32 v65, v65
	v_add_f32_e32 v64, 1.0, v64
	v_add_f32_e32 v65, 1.0, v65
	v_rcp_f32_e32 v64, v64
	v_rcp_f32_e32 v65, v65
	s_nop 0
	v_pk_mul_f32 v[62:63], v[62:63], v[64:65]
	s_nop 0
	v_pk_mul_f32 v[60:61], v[60:61], v[62:63]
	v_mul_f32_e32 v62, 0xbfb8aa3b, v54
	v_mul_f32_e32 v63, 0xbfb8aa3b, v55
	v_exp_f32_e32 v62, v62
	v_exp_f32_e32 v63, v63
	v_add_f32_e32 v62, 1.0, v62
	v_add_f32_e32 v63, 1.0, v63
	v_rcp_f32_e32 v62, v62
	v_rcp_f32_e32 v63, v63
	s_nop 0
	v_pk_mul_f32 v[54:55], v[54:55], v[62:63]
	s_nop 0
	v_pk_mul_f32 v[54:55], v[50:51], v[54:55]
	v_pk_mul_f32 v[50:51], v[56:57], v[66:67] op_sel_hi:[1,0]
	s_nop 0
	v_mul_f32_e32 v56, 0xbfb8aa3b, v50
	v_mul_f32_e32 v57, 0xbfb8aa3b, v51
	v_exp_f32_e32 v56, v56
	v_exp_f32_e32 v57, v57
	v_add_f32_e32 v56, 1.0, v56
	v_add_f32_e32 v57, 1.0, v57
	v_rcp_f32_e32 v56, v56
	v_rcp_f32_e32 v57, v57
	s_nop 0
	v_pk_mul_f32 v[50:51], v[50:51], v[56:57]
	s_nop 0
	v_pk_mul_f32 v[56:57], v[52:53], v[50:51]
	v_cvt_pk_bf16_f32 v52, v54, v55
	v_add_u32_e32 v54, 0x80, v118
	v_mad_i64_i32 v[54:55], s[2:3], v54, s63, v[114:115]
	v_cvt_pk_bf16_f32 v50, v58, v59
	v_cvt_pk_bf16_f32 v51, v60, v61
	v_cvt_pk_bf16_f32 v53, v56, v57
	v_lshl_add_u64 v[54:55], v[54:55], 0, v[116:117]
	global_store_dwordx4 v[54:55], v[50:53], off nt
	s_nop 1
	v_mov_b32_e32 v50, v67
	v_pk_mul_f32 v[46:47], v[46:47], v[50:51] op_sel_hi:[1,0]
	s_nop 0
	v_mul_f32_e32 v51, 0xbfb8aa3b, v46
	v_exp_f32_e32 v51, v51
	s_nop 0
	v_add_f32_e32 v51, 1.0, v51
	v_rcp_f32_e32 v52, v51
	v_mul_f32_e32 v51, 0xbfb8aa3b, v47
	v_exp_f32_e32 v51, v51
	s_nop 0
	v_add_f32_e32 v51, 1.0, v51
	v_rcp_f32_e32 v53, v51
	v_pk_mul_f32 v[42:43], v[42:43], v[50:51] op_sel_hi:[1,0]
	v_pk_mul_f32 v[44:45], v[44:45], v[50:51] op_sel_hi:[1,0]
	v_pk_mul_f32 v[38:39], v[38:39], v[50:51] op_sel_hi:[1,0]
	v_pk_mul_f32 v[46:47], v[46:47], v[52:53]
	v_pk_mul_f32 v[34:35], v[34:35], v[50:51] op_sel_hi:[1,0]
	v_pk_mul_f32 v[42:43], v[42:43], v[46:47]
	v_pk_mul_f32 v[46:47], v[48:49], v[50:51] op_sel_hi:[1,0]
	v_pk_mul_f32 v[36:37], v[36:37], v[50:51] op_sel_hi:[1,0]
	v_mul_f32_e32 v48, 0xbfb8aa3b, v46
	v_mul_f32_e32 v49, 0xbfb8aa3b, v47
	v_exp_f32_e32 v48, v48
	v_exp_f32_e32 v49, v49
	v_add_f32_e32 v48, 1.0, v48
	v_add_f32_e32 v49, 1.0, v49
	v_rcp_f32_e32 v48, v48
	v_rcp_f32_e32 v49, v49
	s_nop 0
	v_pk_mul_f32 v[46:47], v[46:47], v[48:49]
	s_nop 0
	v_pk_mul_f32 v[44:45], v[44:45], v[46:47]
	v_mul_f32_e32 v46, 0xbfb8aa3b, v38
	v_mul_f32_e32 v47, 0xbfb8aa3b, v39
	v_exp_f32_e32 v46, v46
	v_exp_f32_e32 v47, v47
	v_add_f32_e32 v46, 1.0, v46
	v_add_f32_e32 v47, 1.0, v47
	v_rcp_f32_e32 v46, v46
	v_rcp_f32_e32 v47, v47
	s_nop 0
	v_pk_mul_f32 v[38:39], v[38:39], v[46:47]
	s_nop 0
	v_pk_mul_f32 v[38:39], v[34:35], v[38:39]
	v_pk_mul_f32 v[34:35], v[40:41], v[50:51] op_sel_hi:[1,0]
	s_nop 0
	v_mul_f32_e32 v40, 0xbfb8aa3b, v34
	v_mul_f32_e32 v41, 0xbfb8aa3b, v35
	v_exp_f32_e32 v40, v40
	v_exp_f32_e32 v41, v41
	v_add_f32_e32 v40, 1.0, v40
	v_add_f32_e32 v41, 1.0, v41
	v_rcp_f32_e32 v40, v40
	v_rcp_f32_e32 v41, v41
	s_nop 0
	v_pk_mul_f32 v[34:35], v[34:35], v[40:41]
	s_nop 0
	v_pk_mul_f32 v[40:41], v[36:37], v[34:35]
	v_cvt_pk_bf16_f32 v36, v38, v39
	v_add_u32_e32 v38, 0x90, v118
	v_mad_i64_i32 v[38:39], s[2:3], v38, s63, v[114:115]
	v_cvt_pk_bf16_f32 v34, v42, v43
	v_cvt_pk_bf16_f32 v35, v44, v45
	v_cvt_pk_bf16_f32 v37, v40, v41
	v_lshl_add_u64 v[38:39], v[38:39], 0, v[116:117]
	global_store_dwordx4 v[38:39], v[34:37], off nt
	ds_read2_b32 v[34:35], v150 offset0:160 offset1:176
	s_waitcnt lgkmcnt(0)
	v_pk_mul_f32 v[30:31], v[30:31], v[34:35] op_sel_hi:[1,0]
	s_nop 0
	v_mul_f32_e32 v36, 0xbfb8aa3b, v30
	v_mul_f32_e32 v37, 0xbfb8aa3b, v31
	v_exp_f32_e32 v36, v36
	v_exp_f32_e32 v37, v37
	v_pk_mul_f32 v[26:27], v[26:27], v[34:35] op_sel_hi:[1,0]
	v_pk_mul_f32 v[28:29], v[28:29], v[34:35] op_sel_hi:[1,0]
	v_add_f32_e32 v36, 1.0, v36
	v_add_f32_e32 v37, 1.0, v37
	v_rcp_f32_e32 v36, v36
	v_rcp_f32_e32 v37, v37
	v_pk_mul_f32 v[22:23], v[22:23], v[34:35] op_sel_hi:[1,0]
	v_pk_mul_f32 v[18:19], v[18:19], v[34:35] op_sel_hi:[1,0]
	v_pk_mul_f32 v[20:21], v[20:21], v[34:35] op_sel_hi:[1,0]
	v_pk_mul_f32 v[30:31], v[30:31], v[36:37]
	s_nop 0
	v_pk_mul_f32 v[26:27], v[26:27], v[30:31]
	v_pk_mul_f32 v[30:31], v[32:33], v[34:35] op_sel_hi:[1,0]
	s_nop 0
	v_mul_f32_e32 v32, 0xbfb8aa3b, v30
	v_mul_f32_e32 v33, 0xbfb8aa3b, v31
	v_exp_f32_e32 v32, v32
	v_exp_f32_e32 v33, v33
	v_add_f32_e32 v32, 1.0, v32
	v_add_f32_e32 v33, 1.0, v33
	v_rcp_f32_e32 v32, v32
	v_rcp_f32_e32 v33, v33
	s_nop 0
	v_pk_mul_f32 v[30:31], v[30:31], v[32:33]
	s_nop 0
	v_pk_mul_f32 v[28:29], v[28:29], v[30:31]
	v_mul_f32_e32 v30, 0xbfb8aa3b, v22
	v_mul_f32_e32 v31, 0xbfb8aa3b, v23
	v_exp_f32_e32 v30, v30
	v_exp_f32_e32 v31, v31
	v_add_f32_e32 v30, 1.0, v30
	v_add_f32_e32 v31, 1.0, v31
	v_rcp_f32_e32 v30, v30
	v_rcp_f32_e32 v31, v31
	s_nop 0
	v_pk_mul_f32 v[22:23], v[22:23], v[30:31]
	s_nop 0
	v_pk_mul_f32 v[22:23], v[18:19], v[22:23]
	v_pk_mul_f32 v[18:19], v[24:25], v[34:35] op_sel_hi:[1,0]
	s_nop 0
	v_mul_f32_e32 v24, 0xbfb8aa3b, v18
	v_mul_f32_e32 v25, 0xbfb8aa3b, v19
	v_exp_f32_e32 v24, v24
	v_exp_f32_e32 v25, v25
	v_add_f32_e32 v24, 1.0, v24
	v_add_f32_e32 v25, 1.0, v25
	v_rcp_f32_e32 v24, v24
	v_rcp_f32_e32 v25, v25
	s_nop 0
	v_pk_mul_f32 v[18:19], v[18:19], v[24:25]
	s_nop 0
	v_pk_mul_f32 v[24:25], v[20:21], v[18:19]
	v_cvt_pk_bf16_f32 v20, v22, v23
	v_add_u32_e32 v22, 0xa0, v118
	v_mad_i64_i32 v[22:23], s[2:3], v22, s63, v[114:115]
	v_cvt_pk_bf16_f32 v18, v26, v27
	v_cvt_pk_bf16_f32 v19, v28, v29
	v_cvt_pk_bf16_f32 v21, v24, v25
	v_lshl_add_u64 v[22:23], v[22:23], 0, v[116:117]
	global_store_dwordx4 v[22:23], v[18:21], off nt
	s_nop 1
	v_mov_b32_e32 v18, v35
	v_pk_mul_f32 v[14:15], v[14:15], v[18:19] op_sel_hi:[1,0]
	s_nop 0
	v_mul_f32_e32 v19, 0xbfb8aa3b, v14
	v_exp_f32_e32 v19, v19
	s_nop 0
	v_add_f32_e32 v19, 1.0, v19
	v_rcp_f32_e32 v20, v19
	v_mul_f32_e32 v19, 0xbfb8aa3b, v15
	v_exp_f32_e32 v19, v19
	s_nop 0
	v_add_f32_e32 v19, 1.0, v19
	v_rcp_f32_e32 v21, v19
	v_pk_mul_f32 v[10:11], v[10:11], v[18:19] op_sel_hi:[1,0]
	v_pk_mul_f32 v[12:13], v[12:13], v[18:19] op_sel_hi:[1,0]
	v_pk_mul_f32 v[6:7], v[6:7], v[18:19] op_sel_hi:[1,0]
	v_pk_mul_f32 v[14:15], v[14:15], v[20:21]
	v_pk_mul_f32 v[2:3], v[2:3], v[18:19] op_sel_hi:[1,0]
	v_pk_mul_f32 v[10:11], v[10:11], v[14:15]
	v_pk_mul_f32 v[14:15], v[16:17], v[18:19] op_sel_hi:[1,0]
	v_pk_mul_f32 v[4:5], v[4:5], v[18:19] op_sel_hi:[1,0]
	v_mul_f32_e32 v16, 0xbfb8aa3b, v14
	v_mul_f32_e32 v17, 0xbfb8aa3b, v15
	v_exp_f32_e32 v16, v16
	v_exp_f32_e32 v17, v17
	v_add_f32_e32 v16, 1.0, v16
	v_add_f32_e32 v17, 1.0, v17
	v_rcp_f32_e32 v16, v16
	v_rcp_f32_e32 v17, v17
	s_nop 0
	v_pk_mul_f32 v[14:15], v[14:15], v[16:17]
	s_nop 0
	v_pk_mul_f32 v[12:13], v[12:13], v[14:15]
	v_mul_f32_e32 v14, 0xbfb8aa3b, v6
	v_mul_f32_e32 v15, 0xbfb8aa3b, v7
	v_exp_f32_e32 v14, v14
	v_exp_f32_e32 v15, v15
	v_add_f32_e32 v14, 1.0, v14
	v_add_f32_e32 v15, 1.0, v15
	v_rcp_f32_e32 v14, v14
	v_rcp_f32_e32 v15, v15
	s_nop 0
	v_pk_mul_f32 v[6:7], v[6:7], v[14:15]
	s_nop 0
	v_pk_mul_f32 v[6:7], v[2:3], v[6:7]
	v_pk_mul_f32 v[2:3], v[8:9], v[18:19] op_sel_hi:[1,0]
	s_nop 0
	v_mul_f32_e32 v8, 0xbfb8aa3b, v2
	v_mul_f32_e32 v9, 0xbfb8aa3b, v3
	v_exp_f32_e32 v8, v8
	v_exp_f32_e32 v9, v9
	v_add_f32_e32 v8, 1.0, v8
	v_add_f32_e32 v9, 1.0, v9
	v_rcp_f32_e32 v8, v8
	v_rcp_f32_e32 v9, v9
	s_nop 0
	v_pk_mul_f32 v[2:3], v[2:3], v[8:9]
	s_nop 0
	v_pk_mul_f32 v[8:9], v[4:5], v[2:3]
	v_cvt_pk_bf16_f32 v4, v6, v7
	v_add_u32_e32 v6, 0xb0, v118
	v_mad_i64_i32 v[6:7], s[2:3], v6, s63, v[114:115]
	v_cvt_pk_bf16_f32 v2, v10, v11
	v_cvt_pk_bf16_f32 v3, v12, v13
	v_cvt_pk_bf16_f32 v5, v8, v9
	v_lshl_add_u64 v[6:7], v[6:7], 0, v[116:117]
	global_store_dwordx4 v[6:7], v[2:5], off nt
	s_cbranch_vccnz .LBB0_1093
	s_andn2_b64 vcc, exec, s[8:9]
	s_cbranch_vccnz .LBB0_1092
	s_barrier
	s_branch .LBB0_1092
